# gemm_in mainloop rewritten by hand: BK=64 LDS-DMA (global_load_lds_dwordx4) in full 128-B row pieces, 4x16KB LDS units, m-split sub-steps, 1 barrier per 32 MFMA; f16 MFMA f32 acc unchanged
# speedup vs baseline: 1.0310x; 1.0310x over previous
.LBB0_316:
	s_bfe_u32 s0, s9, 0xd0003
	s_mul_i32 s4, s0, 0x2493
	s_lshr_b32 s4, s4, 16
	s_mul_i32 s7, s4, 37
	s_lshr_b32 s8, s7, 8
	s_sub_i32 s8, s4, s8
	s_bfe_u32 s8, s8, 0x70001
	s_bfe_u32 s7, s7, 0x80008
	s_add_i32 s8, s8, s7
	s_bfe_u32 s7, s8, 0x60002
	s_mul_i32 s5, s4, 56
	s_mul_i32 s7, s7, 7
	s_sub_i32 s5, s9, s5
	s_sub_i32 s4, s4, s7
	s_and_b32 s6, s5, 0xffff
	s_mulk_i32 s0, 0xa73
	s_mul_i32 s4, s4, 7
	s_and_b32 s4, s4, 0xff
	s_bfe_u32 s16, s5, 0xd0003
	s_lshr_b32 s0, s0, 6
	s_lshl_b32 s8, s6, 8
	s_add_i32 s16, s16, s4
	s_and_b32 s0, s0, 0xf800
	s_and_b32 s4, s8, 0x700
	s_or_b32 s0, s4, s0
	s_lshl_b32 s4, s16, 19
	s_add_u32 s4, s12, s4
	s_addc_u32 s5, s13, 0
	s_lshl_b32 s6, s0, 12
	v_readlane_b32 s10, v254, 12
	v_readlane_b32 s11, v254, 13
	s_add_u32 s6, s10, s6
	s_addc_u32 s7, s11, 0
	v_lshrrev_b32_e32 v134, 6, v171
	v_and_b32_e32 v135, 63, v171
	v_readfirstlane_b32 s11, v134
	v_lshrrev_b32_e32 v175, 4, v135
	v_and_b32_e32 v128, 7, v135
	v_lshrrev_b32_e32 v129, 3, v135
	s_and_b32 s18, s11, 1
	s_lshl_b32 s18, s18, 2
	v_or_b32_e32 v176, s18, v175
	v_xor_b32_e32 v128, v128, v176
	v_lshlrev_b32_e32 v128, 4, v128
	v_lshl_or_b32 v128, v129, 12, v128
	s_lshl_b32 s18, s11, 15
	v_add_u32_e32 v128, s18, v128
	v_add_u32_e32 v129, 0x20000, v128
	v_add_u32_e32 v130, 0x40000, v128
	v_add_u32_e32 v131, 0x60000, v128
	v_add_u32_e32 v132, 0x80000, v128
	v_add_u32_e32 v133, 0xa0000, v128
	v_and_b32_e32 v134, 15, v135
	v_bfe_u32 v176, v134, 1, 3
	v_xor_b32_e32 v176, v176, v175
	v_lshlrev_b32_e32 v176, 4, v176
	v_lshl_or_b32 v176, v134, 7, v176
	s_and_b32 s18, s11, 1
	s_lshl_b32 s18, s18, 13
	v_add_u32_e32 v175, s18, v176
	s_lshr_b32 s19, s11, 1
	s_lshl_b32 s19, s19, 13
	v_add_u32_e32 v176, s19, v176
	v_xor_b32_e32 v177, 64, v175
	v_xor_b32_e32 v178, 64, v176
	s_lshl_b32 s11, s11, 10
	s_barrier
	s_add_u32 m0, s11, 0x0
	s_nop 0
	global_load_lds_dwordx4 v128, s[4:5]
	s_add_u32 m0, s11, 0x1000
	s_nop 0
	global_load_lds_dwordx4 v129, s[4:5]
	s_add_u32 m0, s11, 0x2000
	s_nop 0
	global_load_lds_dwordx4 v130, s[4:5]
	s_add_u32 m0, s11, 0x3000
	s_nop 0
	global_load_lds_dwordx4 v131, s[4:5]
	s_add_u32 m0, s11, 0x8000
	s_nop 0
	global_load_lds_dwordx4 v128, s[6:7]
	s_add_u32 m0, s11, 0x9000
	s_nop 0
	global_load_lds_dwordx4 v129, s[6:7]
	s_add_u32 m0, s11, 0xa000
	s_nop 0
	global_load_lds_dwordx4 v132, s[6:7]
	s_add_u32 m0, s11, 0xb000
	s_nop 0
	global_load_lds_dwordx4 v133, s[6:7]
	s_add_u32 s18, s6, 0x40000
	s_addc_u32 s19, s7, 0
	s_add_u32 s4, s4, 128
	s_addc_u32 s5, s5, 0
	s_add_u32 s6, s6, 128
	s_addc_u32 s7, s7, 0
	v_mov_b32_e32 v0, 0
	v_mov_b32_e32 v1, v0
	v_mov_b32_e32 v2, v0
	v_mov_b32_e32 v3, v0
	v_mov_b32_e32 v4, v0
	v_mov_b32_e32 v5, v0
	v_mov_b32_e32 v6, v0
	v_mov_b32_e32 v7, v0
	v_mov_b32_e32 v8, v0
	v_mov_b32_e32 v9, v0
	v_mov_b32_e32 v10, v0
	v_mov_b32_e32 v11, v0
	v_mov_b32_e32 v12, v0
	v_mov_b32_e32 v13, v0
	v_mov_b32_e32 v14, v0
	v_mov_b32_e32 v15, v0
	v_mov_b32_e32 v16, v0
	v_mov_b32_e32 v17, v0
	v_mov_b32_e32 v18, v0
	v_mov_b32_e32 v19, v0
	v_mov_b32_e32 v20, v0
	v_mov_b32_e32 v21, v0
	v_mov_b32_e32 v22, v0
	v_mov_b32_e32 v23, v0
	v_mov_b32_e32 v24, v0
	v_mov_b32_e32 v25, v0
	v_mov_b32_e32 v26, v0
	v_mov_b32_e32 v27, v0
	v_mov_b32_e32 v28, v0
	v_mov_b32_e32 v29, v0
	v_mov_b32_e32 v30, v0
	v_mov_b32_e32 v31, v0
	v_mov_b32_e32 v32, v0
	v_mov_b32_e32 v33, v0
	v_mov_b32_e32 v34, v0
	v_mov_b32_e32 v35, v0
	v_mov_b32_e32 v36, v0
	v_mov_b32_e32 v37, v0
	v_mov_b32_e32 v38, v0
	v_mov_b32_e32 v39, v0
	v_mov_b32_e32 v40, v0
	v_mov_b32_e32 v41, v0
	v_mov_b32_e32 v42, v0
	v_mov_b32_e32 v43, v0
	v_mov_b32_e32 v44, v0
	v_mov_b32_e32 v45, v0
	v_mov_b32_e32 v46, v0
	v_mov_b32_e32 v47, v0
	v_mov_b32_e32 v48, v0
	v_mov_b32_e32 v49, v0
	v_mov_b32_e32 v50, v0
	v_mov_b32_e32 v51, v0
	v_mov_b32_e32 v52, v0
	v_mov_b32_e32 v53, v0
	v_mov_b32_e32 v54, v0
	v_mov_b32_e32 v55, v0
	v_mov_b32_e32 v56, v0
	v_mov_b32_e32 v57, v0
	v_mov_b32_e32 v58, v0
	v_mov_b32_e32 v59, v0
	v_mov_b32_e32 v60, v0
	v_mov_b32_e32 v61, v0
	v_mov_b32_e32 v62, v0
	v_mov_b32_e32 v63, v0
	v_mov_b32_e32 v64, v0
	v_mov_b32_e32 v65, v0
	v_mov_b32_e32 v66, v0
	v_mov_b32_e32 v67, v0
	v_mov_b32_e32 v68, v0
	v_mov_b32_e32 v69, v0
	v_mov_b32_e32 v70, v0
	v_mov_b32_e32 v71, v0
	v_mov_b32_e32 v72, v0
	v_mov_b32_e32 v73, v0
	v_mov_b32_e32 v74, v0
	v_mov_b32_e32 v75, v0
	v_mov_b32_e32 v76, v0
	v_mov_b32_e32 v77, v0
	v_mov_b32_e32 v78, v0
	v_mov_b32_e32 v79, v0
	v_mov_b32_e32 v80, v0
	v_mov_b32_e32 v81, v0
	v_mov_b32_e32 v82, v0
	v_mov_b32_e32 v83, v0
	v_mov_b32_e32 v84, v0
	v_mov_b32_e32 v85, v0
	v_mov_b32_e32 v86, v0
	v_mov_b32_e32 v87, v0
	v_mov_b32_e32 v88, v0
	v_mov_b32_e32 v89, v0
	v_mov_b32_e32 v90, v0
	v_mov_b32_e32 v91, v0
	v_mov_b32_e32 v92, v0
	v_mov_b32_e32 v93, v0
	v_mov_b32_e32 v94, v0
	v_mov_b32_e32 v95, v0
	v_mov_b32_e32 v96, v0
	v_mov_b32_e32 v97, v0
	v_mov_b32_e32 v98, v0
	v_mov_b32_e32 v99, v0
	v_mov_b32_e32 v100, v0
	v_mov_b32_e32 v101, v0
	v_mov_b32_e32 v102, v0
	v_mov_b32_e32 v103, v0
	v_mov_b32_e32 v104, v0
	v_mov_b32_e32 v105, v0
	v_mov_b32_e32 v106, v0
	v_mov_b32_e32 v107, v0
	v_mov_b32_e32 v108, v0
	v_mov_b32_e32 v109, v0
	v_mov_b32_e32 v110, v0
	v_mov_b32_e32 v111, v0
	v_mov_b32_e32 v112, v0
	v_mov_b32_e32 v113, v0
	v_mov_b32_e32 v114, v0
	v_mov_b32_e32 v115, v0
	v_mov_b32_e32 v116, v0
	v_mov_b32_e32 v117, v0
	v_mov_b32_e32 v118, v0
	v_mov_b32_e32 v119, v0
	v_mov_b32_e32 v120, v0
	v_mov_b32_e32 v121, v0
	v_mov_b32_e32 v122, v0
	v_mov_b32_e32 v123, v0
	v_mov_b32_e32 v124, v0
	v_mov_b32_e32 v125, v0
	v_mov_b32_e32 v126, v0
	v_mov_b32_e32 v127, v0
	s_mov_b32 s10, 0
.Lgin_loop:
	s_waitcnt vmcnt(0)
	s_barrier
	ds_read_b128 v[230:233], v175 offset:0
	ds_read_b128 v[234:237], v175 offset:2048
	ds_read_b128 v[238:241], v175 offset:4096
	ds_read_b128 v[242:245], v175 offset:6144
	ds_read_b128 v[182:185], v176 offset:32768
	ds_read_b128 v[186:189], v176 offset:34816
	ds_read_b128 v[190:193], v176 offset:36864
	ds_read_b128 v[194:197], v176 offset:38912
	ds_read_b128 v[136:139], v177 offset:0
	ds_read_b128 v[140:143], v177 offset:2048
	ds_read_b128 v[144:147], v177 offset:4096
	ds_read_b128 v[148:151], v177 offset:6144
	s_add_u32 m0, s11, 0xc000
	s_waitcnt lgkmcnt(7)
	v_mfma_f32_16x16x32_f16 v[124:127], v[230:233], v[182:185], v[124:127]
	v_mfma_f32_16x16x32_f16 v[92:95], v[234:237], v[182:185], v[92:95]
	v_mfma_f32_16x16x32_f16 v[60:63], v[238:241], v[182:185], v[60:63]
	v_mfma_f32_16x16x32_f16 v[28:31], v[242:245], v[182:185], v[28:31]
	ds_read_b128 v[198:201], v178 offset:32768
	ds_read_b128 v[202:205], v178 offset:34816
	ds_read_b128 v[222:225], v178 offset:36864
	ds_read_b128 v[226:229], v178 offset:38912
	global_load_lds_dwordx4 v128, s[18:19]
	s_add_u32 m0, s11, 0xd000
	s_waitcnt lgkmcnt(10)
	v_mfma_f32_16x16x32_f16 v[120:123], v[230:233], v[186:189], v[120:123]
	v_mfma_f32_16x16x32_f16 v[88:91], v[234:237], v[186:189], v[88:91]
	v_mfma_f32_16x16x32_f16 v[56:59], v[238:241], v[186:189], v[56:59]
	v_mfma_f32_16x16x32_f16 v[24:27], v[242:245], v[186:189], v[24:27]
	global_load_lds_dwordx4 v129, s[18:19]
	s_add_u32 m0, s11, 0xe000
	s_waitcnt lgkmcnt(9)
	v_mfma_f32_16x16x32_f16 v[116:119], v[230:233], v[190:193], v[116:119]
	v_mfma_f32_16x16x32_f16 v[84:87], v[234:237], v[190:193], v[84:87]
	v_mfma_f32_16x16x32_f16 v[52:55], v[238:241], v[190:193], v[52:55]
	v_mfma_f32_16x16x32_f16 v[20:23], v[242:245], v[190:193], v[20:23]
	global_load_lds_dwordx4 v132, s[18:19]
	s_add_u32 m0, s11, 0xf000
	s_waitcnt lgkmcnt(8)
	v_mfma_f32_16x16x32_f16 v[112:115], v[230:233], v[194:197], v[112:115]
	v_mfma_f32_16x16x32_f16 v[80:83], v[234:237], v[194:197], v[80:83]
	v_mfma_f32_16x16x32_f16 v[48:51], v[238:241], v[194:197], v[48:51]
	v_mfma_f32_16x16x32_f16 v[16:19], v[242:245], v[194:197], v[16:19]
	global_load_lds_dwordx4 v133, s[18:19]
	s_add_u32 m0, s11, 0x4000
	s_waitcnt lgkmcnt(3)
	v_mfma_f32_16x16x32_f16 v[124:127], v[136:139], v[198:201], v[124:127]
	v_mfma_f32_16x16x32_f16 v[92:95], v[140:143], v[198:201], v[92:95]
	v_mfma_f32_16x16x32_f16 v[60:63], v[144:147], v[198:201], v[60:63]
	v_mfma_f32_16x16x32_f16 v[28:31], v[148:151], v[198:201], v[28:31]
	global_load_lds_dwordx4 v128, s[4:5]
	s_add_u32 m0, s11, 0x5000
	s_waitcnt lgkmcnt(2)
	v_mfma_f32_16x16x32_f16 v[120:123], v[136:139], v[202:205], v[120:123]
	v_mfma_f32_16x16x32_f16 v[88:91], v[140:143], v[202:205], v[88:91]
	v_mfma_f32_16x16x32_f16 v[56:59], v[144:147], v[202:205], v[56:59]
	v_mfma_f32_16x16x32_f16 v[24:27], v[148:151], v[202:205], v[24:27]
	global_load_lds_dwordx4 v129, s[4:5]
	s_add_u32 m0, s11, 0x6000
	s_waitcnt lgkmcnt(1)
	v_mfma_f32_16x16x32_f16 v[116:119], v[136:139], v[222:225], v[116:119]
	v_mfma_f32_16x16x32_f16 v[84:87], v[140:143], v[222:225], v[84:87]
	v_mfma_f32_16x16x32_f16 v[52:55], v[144:147], v[222:225], v[52:55]
	v_mfma_f32_16x16x32_f16 v[20:23], v[148:151], v[222:225], v[20:23]
	global_load_lds_dwordx4 v130, s[4:5]
	s_add_u32 m0, s11, 0x7000
	s_waitcnt lgkmcnt(0)
	v_mfma_f32_16x16x32_f16 v[112:115], v[136:139], v[226:229], v[112:115]
	v_mfma_f32_16x16x32_f16 v[80:83], v[140:143], v[226:229], v[80:83]
	v_mfma_f32_16x16x32_f16 v[48:51], v[144:147], v[226:229], v[48:51]
	v_mfma_f32_16x16x32_f16 v[16:19], v[148:151], v[226:229], v[16:19]
	global_load_lds_dwordx4 v131, s[4:5]
	s_add_u32 s18, s18, 128
	s_addc_u32 s19, s19, 0
	s_add_u32 s4, s4, 128
	s_addc_u32 s5, s5, 0
	s_waitcnt vmcnt(4)
	s_barrier
	ds_read_b128 v[230:233], v175 offset:0
	ds_read_b128 v[234:237], v175 offset:2048
	ds_read_b128 v[238:241], v175 offset:4096
	ds_read_b128 v[242:245], v175 offset:6144
	ds_read_b128 v[182:185], v176 offset:49152
	ds_read_b128 v[186:189], v176 offset:51200
	ds_read_b128 v[190:193], v176 offset:53248
	ds_read_b128 v[194:197], v176 offset:55296
	ds_read_b128 v[136:139], v177 offset:0
	ds_read_b128 v[140:143], v177 offset:2048
	ds_read_b128 v[144:147], v177 offset:4096
	ds_read_b128 v[148:151], v177 offset:6144
	s_add_u32 m0, s11, 0x8000
	s_waitcnt lgkmcnt(7)
	v_mfma_f32_16x16x32_f16 v[108:111], v[230:233], v[182:185], v[108:111]
	v_mfma_f32_16x16x32_f16 v[76:79], v[234:237], v[182:185], v[76:79]
	v_mfma_f32_16x16x32_f16 v[44:47], v[238:241], v[182:185], v[44:47]
	v_mfma_f32_16x16x32_f16 v[12:15], v[242:245], v[182:185], v[12:15]
	ds_read_b128 v[198:201], v178 offset:49152
	ds_read_b128 v[202:205], v178 offset:51200
	ds_read_b128 v[222:225], v178 offset:53248
	ds_read_b128 v[226:229], v178 offset:55296
	global_load_lds_dwordx4 v128, s[6:7]
	s_add_u32 m0, s11, 0x9000
	s_waitcnt lgkmcnt(10)
	v_mfma_f32_16x16x32_f16 v[104:107], v[230:233], v[186:189], v[104:107]
	v_mfma_f32_16x16x32_f16 v[72:75], v[234:237], v[186:189], v[72:75]
	v_mfma_f32_16x16x32_f16 v[40:43], v[238:241], v[186:189], v[40:43]
	v_mfma_f32_16x16x32_f16 v[8:11], v[242:245], v[186:189], v[8:11]
	global_load_lds_dwordx4 v129, s[6:7]
	s_add_u32 m0, s11, 0xa000
	s_waitcnt lgkmcnt(9)
	v_mfma_f32_16x16x32_f16 v[100:103], v[230:233], v[190:193], v[100:103]
	v_mfma_f32_16x16x32_f16 v[68:71], v[234:237], v[190:193], v[68:71]
	v_mfma_f32_16x16x32_f16 v[36:39], v[238:241], v[190:193], v[36:39]
	v_mfma_f32_16x16x32_f16 v[4:7], v[242:245], v[190:193], v[4:7]
	global_load_lds_dwordx4 v132, s[6:7]
	s_add_u32 m0, s11, 0xb000
	s_waitcnt lgkmcnt(8)
	v_mfma_f32_16x16x32_f16 v[96:99], v[230:233], v[194:197], v[96:99]
	v_mfma_f32_16x16x32_f16 v[64:67], v[234:237], v[194:197], v[64:67]
	v_mfma_f32_16x16x32_f16 v[32:35], v[238:241], v[194:197], v[32:35]
	v_mfma_f32_16x16x32_f16 v[0:3], v[242:245], v[194:197], v[0:3]
	global_load_lds_dwordx4 v133, s[6:7]
	s_waitcnt lgkmcnt(3)
	v_mfma_f32_16x16x32_f16 v[108:111], v[136:139], v[198:201], v[108:111]
	v_mfma_f32_16x16x32_f16 v[76:79], v[140:143], v[198:201], v[76:79]
	v_mfma_f32_16x16x32_f16 v[44:47], v[144:147], v[198:201], v[44:47]
	v_mfma_f32_16x16x32_f16 v[12:15], v[148:151], v[198:201], v[12:15]
	s_waitcnt lgkmcnt(2)
	v_mfma_f32_16x16x32_f16 v[104:107], v[136:139], v[202:205], v[104:107]
	v_mfma_f32_16x16x32_f16 v[72:75], v[140:143], v[202:205], v[72:75]
	v_mfma_f32_16x16x32_f16 v[40:43], v[144:147], v[202:205], v[40:43]
	v_mfma_f32_16x16x32_f16 v[8:11], v[148:151], v[202:205], v[8:11]
	s_waitcnt lgkmcnt(1)
	v_mfma_f32_16x16x32_f16 v[100:103], v[136:139], v[222:225], v[100:103]
	v_mfma_f32_16x16x32_f16 v[68:71], v[140:143], v[222:225], v[68:71]
	v_mfma_f32_16x16x32_f16 v[36:39], v[144:147], v[222:225], v[36:39]
	v_mfma_f32_16x16x32_f16 v[4:7], v[148:151], v[222:225], v[4:7]
	s_waitcnt lgkmcnt(0)
	v_mfma_f32_16x16x32_f16 v[96:99], v[136:139], v[226:229], v[96:99]
	v_mfma_f32_16x16x32_f16 v[64:67], v[140:143], v[226:229], v[64:67]
	v_mfma_f32_16x16x32_f16 v[32:35], v[144:147], v[226:229], v[32:35]
	v_mfma_f32_16x16x32_f16 v[0:3], v[148:151], v[226:229], v[0:3]
	s_add_u32 s6, s6, 128
	s_addc_u32 s7, s7, 0
	s_waitcnt vmcnt(0)
	s_barrier
	ds_read_b128 v[230:233], v175 offset:16384
	ds_read_b128 v[234:237], v175 offset:18432
	ds_read_b128 v[238:241], v175 offset:20480
	ds_read_b128 v[242:245], v175 offset:22528
	ds_read_b128 v[182:185], v176 offset:32768
	ds_read_b128 v[186:189], v176 offset:34816
	ds_read_b128 v[190:193], v176 offset:36864
	ds_read_b128 v[194:197], v176 offset:38912
	ds_read_b128 v[136:139], v177 offset:16384
	ds_read_b128 v[140:143], v177 offset:18432
	ds_read_b128 v[144:147], v177 offset:20480
	ds_read_b128 v[148:151], v177 offset:22528
	s_add_u32 m0, s11, 0xc000
	s_waitcnt lgkmcnt(7)
	v_mfma_f32_16x16x32_f16 v[124:127], v[230:233], v[182:185], v[124:127]
	v_mfma_f32_16x16x32_f16 v[92:95], v[234:237], v[182:185], v[92:95]
	v_mfma_f32_16x16x32_f16 v[60:63], v[238:241], v[182:185], v[60:63]
	v_mfma_f32_16x16x32_f16 v[28:31], v[242:245], v[182:185], v[28:31]
	ds_read_b128 v[198:201], v178 offset:32768
	ds_read_b128 v[202:205], v178 offset:34816
	ds_read_b128 v[222:225], v178 offset:36864
	ds_read_b128 v[226:229], v178 offset:38912
	global_load_lds_dwordx4 v128, s[18:19]
	s_add_u32 m0, s11, 0xd000
	s_waitcnt lgkmcnt(10)
	v_mfma_f32_16x16x32_f16 v[120:123], v[230:233], v[186:189], v[120:123]
	v_mfma_f32_16x16x32_f16 v[88:91], v[234:237], v[186:189], v[88:91]
	v_mfma_f32_16x16x32_f16 v[56:59], v[238:241], v[186:189], v[56:59]
	v_mfma_f32_16x16x32_f16 v[24:27], v[242:245], v[186:189], v[24:27]
	global_load_lds_dwordx4 v129, s[18:19]
	s_add_u32 m0, s11, 0xe000
	s_waitcnt lgkmcnt(9)
	v_mfma_f32_16x16x32_f16 v[116:119], v[230:233], v[190:193], v[116:119]
	v_mfma_f32_16x16x32_f16 v[84:87], v[234:237], v[190:193], v[84:87]
	v_mfma_f32_16x16x32_f16 v[52:55], v[238:241], v[190:193], v[52:55]
	v_mfma_f32_16x16x32_f16 v[20:23], v[242:245], v[190:193], v[20:23]
	global_load_lds_dwordx4 v132, s[18:19]
	s_add_u32 m0, s11, 0xf000
	s_waitcnt lgkmcnt(8)
	v_mfma_f32_16x16x32_f16 v[112:115], v[230:233], v[194:197], v[112:115]
	v_mfma_f32_16x16x32_f16 v[80:83], v[234:237], v[194:197], v[80:83]
	v_mfma_f32_16x16x32_f16 v[48:51], v[238:241], v[194:197], v[48:51]
	v_mfma_f32_16x16x32_f16 v[16:19], v[242:245], v[194:197], v[16:19]
	global_load_lds_dwordx4 v133, s[18:19]
	s_add_u32 m0, s11, 0x0
	s_waitcnt lgkmcnt(3)
	v_mfma_f32_16x16x32_f16 v[124:127], v[136:139], v[198:201], v[124:127]
	v_mfma_f32_16x16x32_f16 v[92:95], v[140:143], v[198:201], v[92:95]
	v_mfma_f32_16x16x32_f16 v[60:63], v[144:147], v[198:201], v[60:63]
	v_mfma_f32_16x16x32_f16 v[28:31], v[148:151], v[198:201], v[28:31]
	global_load_lds_dwordx4 v128, s[4:5]
	s_add_u32 m0, s11, 0x1000
	s_waitcnt lgkmcnt(2)
	v_mfma_f32_16x16x32_f16 v[120:123], v[136:139], v[202:205], v[120:123]
	v_mfma_f32_16x16x32_f16 v[88:91], v[140:143], v[202:205], v[88:91]
	v_mfma_f32_16x16x32_f16 v[56:59], v[144:147], v[202:205], v[56:59]
	v_mfma_f32_16x16x32_f16 v[24:27], v[148:151], v[202:205], v[24:27]
	global_load_lds_dwordx4 v129, s[4:5]
	s_add_u32 m0, s11, 0x2000
	s_waitcnt lgkmcnt(1)
	v_mfma_f32_16x16x32_f16 v[116:119], v[136:139], v[222:225], v[116:119]
	v_mfma_f32_16x16x32_f16 v[84:87], v[140:143], v[222:225], v[84:87]
	v_mfma_f32_16x16x32_f16 v[52:55], v[144:147], v[222:225], v[52:55]
	v_mfma_f32_16x16x32_f16 v[20:23], v[148:151], v[222:225], v[20:23]
	global_load_lds_dwordx4 v130, s[4:5]
	s_add_u32 m0, s11, 0x3000
	s_waitcnt lgkmcnt(0)
	v_mfma_f32_16x16x32_f16 v[112:115], v[136:139], v[226:229], v[112:115]
	v_mfma_f32_16x16x32_f16 v[80:83], v[140:143], v[226:229], v[80:83]
	v_mfma_f32_16x16x32_f16 v[48:51], v[144:147], v[226:229], v[48:51]
	v_mfma_f32_16x16x32_f16 v[16:19], v[148:151], v[226:229], v[16:19]
	global_load_lds_dwordx4 v131, s[4:5]
	s_add_u32 s18, s18, 128
	s_addc_u32 s19, s19, 0
	s_add_u32 s4, s4, 128
	s_addc_u32 s5, s5, 0
	s_waitcnt vmcnt(4)
	s_barrier
	ds_read_b128 v[230:233], v175 offset:16384
	ds_read_b128 v[234:237], v175 offset:18432
	ds_read_b128 v[238:241], v175 offset:20480
	ds_read_b128 v[242:245], v175 offset:22528
	ds_read_b128 v[182:185], v176 offset:49152
	ds_read_b128 v[186:189], v176 offset:51200
	ds_read_b128 v[190:193], v176 offset:53248
	ds_read_b128 v[194:197], v176 offset:55296
	ds_read_b128 v[136:139], v177 offset:16384
	ds_read_b128 v[140:143], v177 offset:18432
	ds_read_b128 v[144:147], v177 offset:20480
	ds_read_b128 v[148:151], v177 offset:22528
	s_add_u32 m0, s11, 0x8000
	s_waitcnt lgkmcnt(7)
	v_mfma_f32_16x16x32_f16 v[108:111], v[230:233], v[182:185], v[108:111]
	v_mfma_f32_16x16x32_f16 v[76:79], v[234:237], v[182:185], v[76:79]
	v_mfma_f32_16x16x32_f16 v[44:47], v[238:241], v[182:185], v[44:47]
	v_mfma_f32_16x16x32_f16 v[12:15], v[242:245], v[182:185], v[12:15]
	ds_read_b128 v[198:201], v178 offset:49152
	ds_read_b128 v[202:205], v178 offset:51200
	ds_read_b128 v[222:225], v178 offset:53248
	ds_read_b128 v[226:229], v178 offset:55296
	global_load_lds_dwordx4 v128, s[6:7]
	s_add_u32 m0, s11, 0x9000
	s_waitcnt lgkmcnt(10)
	v_mfma_f32_16x16x32_f16 v[104:107], v[230:233], v[186:189], v[104:107]
	v_mfma_f32_16x16x32_f16 v[72:75], v[234:237], v[186:189], v[72:75]
	v_mfma_f32_16x16x32_f16 v[40:43], v[238:241], v[186:189], v[40:43]
	v_mfma_f32_16x16x32_f16 v[8:11], v[242:245], v[186:189], v[8:11]
	global_load_lds_dwordx4 v129, s[6:7]
	s_add_u32 m0, s11, 0xa000
	s_waitcnt lgkmcnt(9)
	v_mfma_f32_16x16x32_f16 v[100:103], v[230:233], v[190:193], v[100:103]
	v_mfma_f32_16x16x32_f16 v[68:71], v[234:237], v[190:193], v[68:71]
	v_mfma_f32_16x16x32_f16 v[36:39], v[238:241], v[190:193], v[36:39]
	v_mfma_f32_16x16x32_f16 v[4:7], v[242:245], v[190:193], v[4:7]
	global_load_lds_dwordx4 v132, s[6:7]
	s_add_u32 m0, s11, 0xb000
	s_waitcnt lgkmcnt(8)
	v_mfma_f32_16x16x32_f16 v[96:99], v[230:233], v[194:197], v[96:99]
	v_mfma_f32_16x16x32_f16 v[64:67], v[234:237], v[194:197], v[64:67]
	v_mfma_f32_16x16x32_f16 v[32:35], v[238:241], v[194:197], v[32:35]
	v_mfma_f32_16x16x32_f16 v[0:3], v[242:245], v[194:197], v[0:3]
	global_load_lds_dwordx4 v133, s[6:7]
	s_waitcnt lgkmcnt(3)
	v_mfma_f32_16x16x32_f16 v[108:111], v[136:139], v[198:201], v[108:111]
	v_mfma_f32_16x16x32_f16 v[76:79], v[140:143], v[198:201], v[76:79]
	v_mfma_f32_16x16x32_f16 v[44:47], v[144:147], v[198:201], v[44:47]
	v_mfma_f32_16x16x32_f16 v[12:15], v[148:151], v[198:201], v[12:15]
	s_waitcnt lgkmcnt(2)
	v_mfma_f32_16x16x32_f16 v[104:107], v[136:139], v[202:205], v[104:107]
	v_mfma_f32_16x16x32_f16 v[72:75], v[140:143], v[202:205], v[72:75]
	v_mfma_f32_16x16x32_f16 v[40:43], v[144:147], v[202:205], v[40:43]
	v_mfma_f32_16x16x32_f16 v[8:11], v[148:151], v[202:205], v[8:11]
	s_waitcnt lgkmcnt(1)
	v_mfma_f32_16x16x32_f16 v[100:103], v[136:139], v[222:225], v[100:103]
	v_mfma_f32_16x16x32_f16 v[68:71], v[140:143], v[222:225], v[68:71]
	v_mfma_f32_16x16x32_f16 v[36:39], v[144:147], v[222:225], v[36:39]
	v_mfma_f32_16x16x32_f16 v[4:7], v[148:151], v[222:225], v[4:7]
	s_waitcnt lgkmcnt(0)
	v_mfma_f32_16x16x32_f16 v[96:99], v[136:139], v[226:229], v[96:99]
	v_mfma_f32_16x16x32_f16 v[64:67], v[140:143], v[226:229], v[64:67]
	v_mfma_f32_16x16x32_f16 v[32:35], v[144:147], v[226:229], v[32:35]
	v_mfma_f32_16x16x32_f16 v[0:3], v[148:151], v[226:229], v[0:3]
	s_add_u32 s6, s6, 128
	s_addc_u32 s7, s7, 0
	s_add_i32 s10, s10, 1
	s_cmp_lt_u32 s10, 15
	s_cbranch_scc1 .Lgin_loop
	s_waitcnt vmcnt(0)
	s_barrier
	ds_read_b128 v[230:233], v175 offset:0
	ds_read_b128 v[234:237], v175 offset:2048
	ds_read_b128 v[238:241], v175 offset:4096
	ds_read_b128 v[242:245], v175 offset:6144
	ds_read_b128 v[182:185], v176 offset:32768
	ds_read_b128 v[186:189], v176 offset:34816
	ds_read_b128 v[190:193], v176 offset:36864
	ds_read_b128 v[194:197], v176 offset:38912
	ds_read_b128 v[136:139], v177 offset:0
	ds_read_b128 v[140:143], v177 offset:2048
	ds_read_b128 v[144:147], v177 offset:4096
	ds_read_b128 v[148:151], v177 offset:6144
	s_add_u32 m0, s11, 0xc000
	s_waitcnt lgkmcnt(7)
	v_mfma_f32_16x16x32_f16 v[124:127], v[230:233], v[182:185], v[124:127]
	v_mfma_f32_16x16x32_f16 v[92:95], v[234:237], v[182:185], v[92:95]
	v_mfma_f32_16x16x32_f16 v[60:63], v[238:241], v[182:185], v[60:63]
	v_mfma_f32_16x16x32_f16 v[28:31], v[242:245], v[182:185], v[28:31]
	ds_read_b128 v[198:201], v178 offset:32768
	ds_read_b128 v[202:205], v178 offset:34816
	ds_read_b128 v[222:225], v178 offset:36864
	ds_read_b128 v[226:229], v178 offset:38912
	global_load_lds_dwordx4 v128, s[18:19]
	s_add_u32 m0, s11, 0xd000
	s_waitcnt lgkmcnt(10)
	v_mfma_f32_16x16x32_f16 v[120:123], v[230:233], v[186:189], v[120:123]
	v_mfma_f32_16x16x32_f16 v[88:91], v[234:237], v[186:189], v[88:91]
	v_mfma_f32_16x16x32_f16 v[56:59], v[238:241], v[186:189], v[56:59]
	v_mfma_f32_16x16x32_f16 v[24:27], v[242:245], v[186:189], v[24:27]
	global_load_lds_dwordx4 v129, s[18:19]
	s_add_u32 m0, s11, 0xe000
	s_waitcnt lgkmcnt(9)
	v_mfma_f32_16x16x32_f16 v[116:119], v[230:233], v[190:193], v[116:119]
	v_mfma_f32_16x16x32_f16 v[84:87], v[234:237], v[190:193], v[84:87]
	v_mfma_f32_16x16x32_f16 v[52:55], v[238:241], v[190:193], v[52:55]
	v_mfma_f32_16x16x32_f16 v[20:23], v[242:245], v[190:193], v[20:23]
	global_load_lds_dwordx4 v132, s[18:19]
	s_add_u32 m0, s11, 0xf000
	s_waitcnt lgkmcnt(8)
	v_mfma_f32_16x16x32_f16 v[112:115], v[230:233], v[194:197], v[112:115]
	v_mfma_f32_16x16x32_f16 v[80:83], v[234:237], v[194:197], v[80:83]
	v_mfma_f32_16x16x32_f16 v[48:51], v[238:241], v[194:197], v[48:51]
	v_mfma_f32_16x16x32_f16 v[16:19], v[242:245], v[194:197], v[16:19]
	global_load_lds_dwordx4 v133, s[18:19]
	s_add_u32 m0, s11, 0x4000
	s_waitcnt lgkmcnt(3)
	v_mfma_f32_16x16x32_f16 v[124:127], v[136:139], v[198:201], v[124:127]
	v_mfma_f32_16x16x32_f16 v[92:95], v[140:143], v[198:201], v[92:95]
	v_mfma_f32_16x16x32_f16 v[60:63], v[144:147], v[198:201], v[60:63]
	v_mfma_f32_16x16x32_f16 v[28:31], v[148:151], v[198:201], v[28:31]
	global_load_lds_dwordx4 v128, s[4:5]
	s_add_u32 m0, s11, 0x5000
	s_waitcnt lgkmcnt(2)
	v_mfma_f32_16x16x32_f16 v[120:123], v[136:139], v[202:205], v[120:123]
	v_mfma_f32_16x16x32_f16 v[88:91], v[140:143], v[202:205], v[88:91]
	v_mfma_f32_16x16x32_f16 v[56:59], v[144:147], v[202:205], v[56:59]
	v_mfma_f32_16x16x32_f16 v[24:27], v[148:151], v[202:205], v[24:27]
	global_load_lds_dwordx4 v129, s[4:5]
	s_add_u32 m0, s11, 0x6000
	s_waitcnt lgkmcnt(1)
	v_mfma_f32_16x16x32_f16 v[116:119], v[136:139], v[222:225], v[116:119]
	v_mfma_f32_16x16x32_f16 v[84:87], v[140:143], v[222:225], v[84:87]
	v_mfma_f32_16x16x32_f16 v[52:55], v[144:147], v[222:225], v[52:55]
	v_mfma_f32_16x16x32_f16 v[20:23], v[148:151], v[222:225], v[20:23]
	global_load_lds_dwordx4 v130, s[4:5]
	s_add_u32 m0, s11, 0x7000
	s_waitcnt lgkmcnt(0)
	v_mfma_f32_16x16x32_f16 v[112:115], v[136:139], v[226:229], v[112:115]
	v_mfma_f32_16x16x32_f16 v[80:83], v[140:143], v[226:229], v[80:83]
	v_mfma_f32_16x16x32_f16 v[48:51], v[144:147], v[226:229], v[48:51]
	v_mfma_f32_16x16x32_f16 v[16:19], v[148:151], v[226:229], v[16:19]
	global_load_lds_dwordx4 v131, s[4:5]
	s_add_u32 s18, s18, 128
	s_addc_u32 s19, s19, 0
	s_add_u32 s4, s4, 128
	s_addc_u32 s5, s5, 0
	s_waitcnt vmcnt(4)
	s_barrier
	ds_read_b128 v[230:233], v175 offset:0
	ds_read_b128 v[234:237], v175 offset:2048
	ds_read_b128 v[238:241], v175 offset:4096
	ds_read_b128 v[242:245], v175 offset:6144
	ds_read_b128 v[182:185], v176 offset:49152
	ds_read_b128 v[186:189], v176 offset:51200
	ds_read_b128 v[190:193], v176 offset:53248
	ds_read_b128 v[194:197], v176 offset:55296
	ds_read_b128 v[136:139], v177 offset:0
	ds_read_b128 v[140:143], v177 offset:2048
	ds_read_b128 v[144:147], v177 offset:4096
	ds_read_b128 v[148:151], v177 offset:6144
	s_add_u32 m0, s11, 0x8000
	s_waitcnt lgkmcnt(7)
	v_mfma_f32_16x16x32_f16 v[108:111], v[230:233], v[182:185], v[108:111]
	v_mfma_f32_16x16x32_f16 v[76:79], v[234:237], v[182:185], v[76:79]
	v_mfma_f32_16x16x32_f16 v[44:47], v[238:241], v[182:185], v[44:47]
	v_mfma_f32_16x16x32_f16 v[12:15], v[242:245], v[182:185], v[12:15]
	ds_read_b128 v[198:201], v178 offset:49152
	ds_read_b128 v[202:205], v178 offset:51200
	ds_read_b128 v[222:225], v178 offset:53248
	ds_read_b128 v[226:229], v178 offset:55296
	global_load_lds_dwordx4 v128, s[6:7]
	s_add_u32 m0, s11, 0x9000
	s_waitcnt lgkmcnt(10)
	v_mfma_f32_16x16x32_f16 v[104:107], v[230:233], v[186:189], v[104:107]
	v_mfma_f32_16x16x32_f16 v[72:75], v[234:237], v[186:189], v[72:75]
	v_mfma_f32_16x16x32_f16 v[40:43], v[238:241], v[186:189], v[40:43]
	v_mfma_f32_16x16x32_f16 v[8:11], v[242:245], v[186:189], v[8:11]
	global_load_lds_dwordx4 v129, s[6:7]
	s_add_u32 m0, s11, 0xa000
	s_waitcnt lgkmcnt(9)
	v_mfma_f32_16x16x32_f16 v[100:103], v[230:233], v[190:193], v[100:103]
	v_mfma_f32_16x16x32_f16 v[68:71], v[234:237], v[190:193], v[68:71]
	v_mfma_f32_16x16x32_f16 v[36:39], v[238:241], v[190:193], v[36:39]
	v_mfma_f32_16x16x32_f16 v[4:7], v[242:245], v[190:193], v[4:7]
	global_load_lds_dwordx4 v132, s[6:7]
	s_add_u32 m0, s11, 0xb000
	s_waitcnt lgkmcnt(8)
	v_mfma_f32_16x16x32_f16 v[96:99], v[230:233], v[194:197], v[96:99]
	v_mfma_f32_16x16x32_f16 v[64:67], v[234:237], v[194:197], v[64:67]
	v_mfma_f32_16x16x32_f16 v[32:35], v[238:241], v[194:197], v[32:35]
	v_mfma_f32_16x16x32_f16 v[0:3], v[242:245], v[194:197], v[0:3]
	global_load_lds_dwordx4 v133, s[6:7]
	s_waitcnt lgkmcnt(3)
	v_mfma_f32_16x16x32_f16 v[108:111], v[136:139], v[198:201], v[108:111]
	v_mfma_f32_16x16x32_f16 v[76:79], v[140:143], v[198:201], v[76:79]
	v_mfma_f32_16x16x32_f16 v[44:47], v[144:147], v[198:201], v[44:47]
	v_mfma_f32_16x16x32_f16 v[12:15], v[148:151], v[198:201], v[12:15]
	s_waitcnt lgkmcnt(2)
	v_mfma_f32_16x16x32_f16 v[104:107], v[136:139], v[202:205], v[104:107]
	v_mfma_f32_16x16x32_f16 v[72:75], v[140:143], v[202:205], v[72:75]
	v_mfma_f32_16x16x32_f16 v[40:43], v[144:147], v[202:205], v[40:43]
	v_mfma_f32_16x16x32_f16 v[8:11], v[148:151], v[202:205], v[8:11]
	s_waitcnt lgkmcnt(1)
	v_mfma_f32_16x16x32_f16 v[100:103], v[136:139], v[222:225], v[100:103]
	v_mfma_f32_16x16x32_f16 v[68:71], v[140:143], v[222:225], v[68:71]
	v_mfma_f32_16x16x32_f16 v[36:39], v[144:147], v[222:225], v[36:39]
	v_mfma_f32_16x16x32_f16 v[4:7], v[148:151], v[222:225], v[4:7]
	s_waitcnt lgkmcnt(0)
	v_mfma_f32_16x16x32_f16 v[96:99], v[136:139], v[226:229], v[96:99]
	v_mfma_f32_16x16x32_f16 v[64:67], v[140:143], v[226:229], v[64:67]
	v_mfma_f32_16x16x32_f16 v[32:35], v[144:147], v[226:229], v[32:35]
	v_mfma_f32_16x16x32_f16 v[0:3], v[148:151], v[226:229], v[0:3]
	s_add_u32 s6, s6, 128
	s_addc_u32 s7, s7, 0
	s_waitcnt vmcnt(0)
	s_barrier
	ds_read_b128 v[230:233], v175 offset:16384
	ds_read_b128 v[234:237], v175 offset:18432
	ds_read_b128 v[238:241], v175 offset:20480
	ds_read_b128 v[242:245], v175 offset:22528
	ds_read_b128 v[182:185], v176 offset:32768
	ds_read_b128 v[186:189], v176 offset:34816
	ds_read_b128 v[190:193], v176 offset:36864
	ds_read_b128 v[194:197], v176 offset:38912
	ds_read_b128 v[136:139], v177 offset:16384
	ds_read_b128 v[140:143], v177 offset:18432
	ds_read_b128 v[144:147], v177 offset:20480
	ds_read_b128 v[148:151], v177 offset:22528
	s_add_u32 m0, s11, 0xc000
	s_waitcnt lgkmcnt(7)
	v_mfma_f32_16x16x32_f16 v[124:127], v[230:233], v[182:185], v[124:127]
	v_mfma_f32_16x16x32_f16 v[92:95], v[234:237], v[182:185], v[92:95]
	v_mfma_f32_16x16x32_f16 v[60:63], v[238:241], v[182:185], v[60:63]
	v_mfma_f32_16x16x32_f16 v[28:31], v[242:245], v[182:185], v[28:31]
	ds_read_b128 v[198:201], v178 offset:32768
	ds_read_b128 v[202:205], v178 offset:34816
	ds_read_b128 v[222:225], v178 offset:36864
	ds_read_b128 v[226:229], v178 offset:38912
	global_load_lds_dwordx4 v128, s[18:19]
	s_add_u32 m0, s11, 0xd000
	s_waitcnt lgkmcnt(10)
	v_mfma_f32_16x16x32_f16 v[120:123], v[230:233], v[186:189], v[120:123]
	v_mfma_f32_16x16x32_f16 v[88:91], v[234:237], v[186:189], v[88:91]
	v_mfma_f32_16x16x32_f16 v[56:59], v[238:241], v[186:189], v[56:59]
	v_mfma_f32_16x16x32_f16 v[24:27], v[242:245], v[186:189], v[24:27]
	global_load_lds_dwordx4 v129, s[18:19]
	s_add_u32 m0, s11, 0xe000
	s_waitcnt lgkmcnt(9)
	v_mfma_f32_16x16x32_f16 v[116:119], v[230:233], v[190:193], v[116:119]
	v_mfma_f32_16x16x32_f16 v[84:87], v[234:237], v[190:193], v[84:87]
	v_mfma_f32_16x16x32_f16 v[52:55], v[238:241], v[190:193], v[52:55]
	v_mfma_f32_16x16x32_f16 v[20:23], v[242:245], v[190:193], v[20:23]
	global_load_lds_dwordx4 v132, s[18:19]
	s_add_u32 m0, s11, 0xf000
	s_waitcnt lgkmcnt(8)
	v_mfma_f32_16x16x32_f16 v[112:115], v[230:233], v[194:197], v[112:115]
	v_mfma_f32_16x16x32_f16 v[80:83], v[234:237], v[194:197], v[80:83]
	v_mfma_f32_16x16x32_f16 v[48:51], v[238:241], v[194:197], v[48:51]
	v_mfma_f32_16x16x32_f16 v[16:19], v[242:245], v[194:197], v[16:19]
	global_load_lds_dwordx4 v133, s[18:19]
	s_waitcnt lgkmcnt(3)
	v_mfma_f32_16x16x32_f16 v[124:127], v[136:139], v[198:201], v[124:127]
	v_mfma_f32_16x16x32_f16 v[92:95], v[140:143], v[198:201], v[92:95]
	v_mfma_f32_16x16x32_f16 v[60:63], v[144:147], v[198:201], v[60:63]
	v_mfma_f32_16x16x32_f16 v[28:31], v[148:151], v[198:201], v[28:31]
	s_waitcnt lgkmcnt(2)
	v_mfma_f32_16x16x32_f16 v[120:123], v[136:139], v[202:205], v[120:123]
	v_mfma_f32_16x16x32_f16 v[88:91], v[140:143], v[202:205], v[88:91]
	v_mfma_f32_16x16x32_f16 v[56:59], v[144:147], v[202:205], v[56:59]
	v_mfma_f32_16x16x32_f16 v[24:27], v[148:151], v[202:205], v[24:27]
	s_waitcnt lgkmcnt(1)
	v_mfma_f32_16x16x32_f16 v[116:119], v[136:139], v[222:225], v[116:119]
	v_mfma_f32_16x16x32_f16 v[84:87], v[140:143], v[222:225], v[84:87]
	v_mfma_f32_16x16x32_f16 v[52:55], v[144:147], v[222:225], v[52:55]
	v_mfma_f32_16x16x32_f16 v[20:23], v[148:151], v[222:225], v[20:23]
	s_waitcnt lgkmcnt(0)
	v_mfma_f32_16x16x32_f16 v[112:115], v[136:139], v[226:229], v[112:115]
	v_mfma_f32_16x16x32_f16 v[80:83], v[140:143], v[226:229], v[80:83]
	v_mfma_f32_16x16x32_f16 v[48:51], v[144:147], v[226:229], v[48:51]
	v_mfma_f32_16x16x32_f16 v[16:19], v[148:151], v[226:229], v[16:19]
	s_waitcnt vmcnt(0)
	s_barrier
	ds_read_b128 v[230:233], v175 offset:16384
	ds_read_b128 v[234:237], v175 offset:18432
	ds_read_b128 v[238:241], v175 offset:20480
	ds_read_b128 v[242:245], v175 offset:22528
	ds_read_b128 v[182:185], v176 offset:49152
	ds_read_b128 v[186:189], v176 offset:51200
	ds_read_b128 v[190:193], v176 offset:53248
	ds_read_b128 v[194:197], v176 offset:55296
	ds_read_b128 v[136:139], v177 offset:16384
	ds_read_b128 v[140:143], v177 offset:18432
	ds_read_b128 v[144:147], v177 offset:20480
	ds_read_b128 v[148:151], v177 offset:22528
	s_waitcnt lgkmcnt(7)
	v_mfma_f32_16x16x32_f16 v[108:111], v[230:233], v[182:185], v[108:111]
	v_mfma_f32_16x16x32_f16 v[76:79], v[234:237], v[182:185], v[76:79]
	v_mfma_f32_16x16x32_f16 v[44:47], v[238:241], v[182:185], v[44:47]
	v_mfma_f32_16x16x32_f16 v[12:15], v[242:245], v[182:185], v[12:15]
	ds_read_b128 v[198:201], v178 offset:49152
	ds_read_b128 v[202:205], v178 offset:51200
	ds_read_b128 v[222:225], v178 offset:53248
	ds_read_b128 v[226:229], v178 offset:55296
	s_waitcnt lgkmcnt(10)
	v_mfma_f32_16x16x32_f16 v[104:107], v[230:233], v[186:189], v[104:107]
	v_mfma_f32_16x16x32_f16 v[72:75], v[234:237], v[186:189], v[72:75]
	v_mfma_f32_16x16x32_f16 v[40:43], v[238:241], v[186:189], v[40:43]
	v_mfma_f32_16x16x32_f16 v[8:11], v[242:245], v[186:189], v[8:11]
	s_waitcnt lgkmcnt(9)
	v_mfma_f32_16x16x32_f16 v[100:103], v[230:233], v[190:193], v[100:103]
	v_mfma_f32_16x16x32_f16 v[68:71], v[234:237], v[190:193], v[68:71]
	v_mfma_f32_16x16x32_f16 v[36:39], v[238:241], v[190:193], v[36:39]
	v_mfma_f32_16x16x32_f16 v[4:7], v[242:245], v[190:193], v[4:7]
	s_waitcnt lgkmcnt(8)
	v_mfma_f32_16x16x32_f16 v[96:99], v[230:233], v[194:197], v[96:99]
	v_mfma_f32_16x16x32_f16 v[64:67], v[234:237], v[194:197], v[64:67]
	v_mfma_f32_16x16x32_f16 v[32:35], v[238:241], v[194:197], v[32:35]
	v_mfma_f32_16x16x32_f16 v[0:3], v[242:245], v[194:197], v[0:3]
	s_waitcnt lgkmcnt(3)
	v_mfma_f32_16x16x32_f16 v[108:111], v[136:139], v[198:201], v[108:111]
	v_mfma_f32_16x16x32_f16 v[76:79], v[140:143], v[198:201], v[76:79]
	v_mfma_f32_16x16x32_f16 v[44:47], v[144:147], v[198:201], v[44:47]
	v_mfma_f32_16x16x32_f16 v[12:15], v[148:151], v[198:201], v[12:15]
	s_waitcnt lgkmcnt(2)
	v_mfma_f32_16x16x32_f16 v[104:107], v[136:139], v[202:205], v[104:107]
	v_mfma_f32_16x16x32_f16 v[72:75], v[140:143], v[202:205], v[72:75]
	v_mfma_f32_16x16x32_f16 v[40:43], v[144:147], v[202:205], v[40:43]
	v_mfma_f32_16x16x32_f16 v[8:11], v[148:151], v[202:205], v[8:11]
	s_waitcnt lgkmcnt(1)
	v_mfma_f32_16x16x32_f16 v[100:103], v[136:139], v[222:225], v[100:103]
	v_mfma_f32_16x16x32_f16 v[68:71], v[140:143], v[222:225], v[68:71]
	v_mfma_f32_16x16x32_f16 v[36:39], v[144:147], v[222:225], v[36:39]
	v_mfma_f32_16x16x32_f16 v[4:7], v[148:151], v[222:225], v[4:7]
	s_waitcnt lgkmcnt(0)
	v_mfma_f32_16x16x32_f16 v[96:99], v[136:139], v[226:229], v[96:99]
	v_mfma_f32_16x16x32_f16 v[64:67], v[140:143], v[226:229], v[64:67]
	v_mfma_f32_16x16x32_f16 v[32:35], v[144:147], v[226:229], v[32:35]
	v_mfma_f32_16x16x32_f16 v[0:3], v[148:151], v[226:229], v[0:3]
	s_nop 7
	s_cmpk_lt_u32 s9, 0x620
	s_cselect_b64 s[44:45], -1, 0
	s_cmpk_gt_u32 s9, 0x61f
	s_cselect_b64 s[4:5], -1, 0
	s_cmp_lt_u32 s16, 6
	s_cselect_b64 s[6:7], -1, 0
	s_and_b64 s[4:5], s[4:5], s[6:7]
	s_and_b64 vcc, exec, s[4:5]
	s_cbranch_vccz .LBB0_320
	v_add_u32_e32 v128, s8, v174
	s_movk_i32 s4, 0x380
	v_and_or_b32 v128, v128, s4, v166
	v_readlane_b32 s4, v254, 41
	v_lshl_or_b32 v168, v128, 9, v180
	v_readlane_b32 s5, v254, 42
	s_nop 4
	global_load_dwordx4 v[130:133], v168, s[4:5] offset:16
	global_load_dwordx4 v[152:155], v168, s[4:5]
	v_lshl_add_u64 v[128:129], s[4:5], 0, v[168:169]
	s_waitcnt vmcnt(1)
	v_mul_f32_e32 v158, v62, v131
	s_waitcnt vmcnt(0)
	v_mov_b32_e32 v150, v153
	v_mov_b32_e32 v153, v154
	v_mul_f32_e32 v154, v126, v130
	v_mul_f32_e32 v160, v126, v131
	v_mul_f32_e32 v130, v62, v130
	v_mov_b32_e32 v62, v127
	v_mov_b32_e32 v126, v63
	v_mov_b32_e32 v151, v155
	v_pk_mul_f32 v[162:163], v[62:63], v[132:133]
	v_pk_mul_f32 v[62:63], v[126:127], v[132:133]
	v_pk_mul_f32 v[156:157], v[124:125], v[150:151]
	v_pk_mul_f32 v[150:151], v[60:61], v[150:151]
	v_mov_b32_e32 v155, v162
	v_mov_b32_e32 v159, v163
	v_mov_b32_e32 v131, v62
	v_mov_b32_e32 v161, v63
	v_pk_fma_f32 v[124:125], v[124:125], v[152:153], v[150:151] neg_lo:[0,0,1] neg_hi:[0,0,1]
	v_pk_add_f32 v[150:151], v[154:155], v[158:159] neg_lo:[0,1] neg_hi:[0,1]
	v_pk_fma_f32 v[60:61], v[60:61], v[152:153], v[156:157]
	v_pk_add_f32 v[62:63], v[130:131], v[160:161]
	global_load_dwordx4 v[130:133], v168, s[4:5] offset:144
	global_load_dwordx4 v[154:157], v168, s[4:5] offset:128
	s_mov_b64 s[4:5], 0x2080
	s_waitcnt vmcnt(1)
	v_mul_f32_e32 v152, v94, v130
	s_waitcnt vmcnt(0)
	v_mov_b32_e32 v126, v155
	v_mov_b32_e32 v127, v157
	v_pk_mul_f32 v[158:159], v[92:93], v[126:127]
	v_mov_b32_e32 v155, v156
	v_pk_mul_f32 v[126:127], v[28:29], v[126:127]
	v_mul_f32_e32 v156, v30, v131
	v_mul_f32_e32 v160, v94, v131
	v_mul_f32_e32 v130, v30, v130
	v_mov_b32_e32 v30, v95
	v_mov_b32_e32 v94, v31
	v_pk_mul_f32 v[162:163], v[30:31], v[132:133]
	v_pk_fma_f32 v[92:93], v[92:93], v[154:155], v[126:127] neg_lo:[0,0,1] neg_hi:[0,0,1]
	v_pk_mul_f32 v[30:31], v[94:95], v[132:133]
	v_add_co_u32_e32 v126, vcc, s33, v128
	v_mov_b32_e32 v153, v162
	v_mov_b32_e32 v157, v163
	v_mov_b32_e32 v131, v30
	v_mov_b32_e32 v161, v31
	v_addc_co_u32_e32 v127, vcc, 0, v129, vcc
	v_pk_add_f32 v[152:153], v[152:153], v[156:157] neg_lo:[0,1] neg_hi:[0,1]
	v_pk_fma_f32 v[28:29], v[28:29], v[154:155], v[158:159]
	v_pk_add_f32 v[30:31], v[130:131], v[160:161]
	v_lshl_add_u64 v[94:95], v[128:129], 0, s[26:27]
	global_load_dwordx4 v[130:133], v[126:127], off
	global_load_dwordx4 v[154:157], v[94:95], off offset:16
	s_waitcnt vmcnt(1)
	v_mov_b32_e32 v94, v131
	s_waitcnt vmcnt(0)
	v_mul_f32_e32 v160, v58, v155
	v_mul_f32_e32 v164, v58, v154
	v_mov_b32_e32 v58, v123
	v_mov_b32_e32 v95, v133
	v_mov_b32_e32 v131, v132
	v_mul_f32_e32 v132, v122, v154
	v_mul_f32_e32 v162, v122, v155
	v_pk_mul_f32 v[154:155], v[58:59], v[156:157]
	v_pk_mul_f32 v[158:159], v[120:121], v[94:95]
	v_pk_mul_f32 v[94:95], v[56:57], v[94:95]
	v_mov_b32_e32 v133, v154
	v_mov_b32_e32 v161, v155
	v_mov_b32_e32 v122, v59
	v_pk_fma_f32 v[120:121], v[120:121], v[130:131], v[94:95] neg_lo:[0,0,1] neg_hi:[0,0,1]
	v_pk_add_f32 v[154:155], v[132:133], v[160:161] neg_lo:[0,1] neg_hi:[0,1]
	v_pk_mul_f32 v[58:59], v[122:123], v[156:157]
	v_pk_fma_f32 v[56:57], v[56:57], v[130:131], v[158:159]
	v_lshl_add_u64 v[94:95], v[128:129], 0, s[4:5]
	global_load_dwordx4 v[130:133], v[126:127], off offset:128
	global_load_dwordx4 v[156:159], v[94:95], off offset:16
	v_mov_b32_e32 v165, v58
	v_mov_b32_e32 v163, v59
	v_pk_add_f32 v[58:59], v[164:165], v[162:163]
	s_mov_b64 s[4:5], 0x4080
	s_waitcnt vmcnt(1)
	v_mov_b32_e32 v94, v131
	v_mov_b32_e32 v131, v132
	s_waitcnt vmcnt(0)
	v_mul_f32_e32 v126, v90, v156
	v_mul_f32_e32 v132, v26, v157
	v_mul_f32_e32 v160, v90, v157
	v_mul_f32_e32 v156, v26, v156
	v_mov_b32_e32 v26, v91
	v_mov_b32_e32 v90, v27
	v_mov_b32_e32 v95, v133
	v_pk_mul_f32 v[162:163], v[26:27], v[158:159]
	v_pk_mul_f32 v[26:27], v[90:91], v[158:159]
	v_add_co_u32_e32 v90, vcc, s97, v128
	v_pk_mul_f32 v[122:123], v[88:89], v[94:95]
	v_pk_mul_f32 v[94:95], v[24:25], v[94:95]
	v_mov_b32_e32 v127, v162
	v_mov_b32_e32 v133, v163
	v_mov_b32_e32 v157, v26
	v_mov_b32_e32 v161, v27
	v_addc_co_u32_e32 v91, vcc, 0, v129, vcc
	v_pk_fma_f32 v[88:89], v[88:89], v[130:131], v[94:95] neg_lo:[0,0,1] neg_hi:[0,0,1]
	v_pk_add_f32 v[94:95], v[126:127], v[132:133] neg_lo:[0,1] neg_hi:[0,1]
	v_pk_fma_f32 v[24:25], v[24:25], v[130:131], v[122:123]
	v_pk_add_f32 v[26:27], v[156:157], v[160:161]
	v_lshl_add_u64 v[122:123], v[128:129], 0, s[84:85]
	global_load_dwordx4 v[130:133], v[90:91], off
	global_load_dwordx4 v[156:159], v[122:123], off offset:16
	s_waitcnt vmcnt(1)
	v_mov_b32_e32 v122, v131
	v_mov_b32_e32 v131, v132
	s_waitcnt vmcnt(0)
	v_mul_f32_e32 v132, v118, v156
	v_mul_f32_e32 v160, v54, v157
	v_mul_f32_e32 v162, v118, v157
	v_mul_f32_e32 v156, v54, v156
	v_mov_b32_e32 v54, v119
	v_mov_b32_e32 v118, v55
	v_mov_b32_e32 v123, v133
	v_pk_mul_f32 v[164:165], v[54:55], v[158:159]
	v_pk_mul_f32 v[54:55], v[118:119], v[158:159]
	v_pk_mul_f32 v[126:127], v[116:117], v[122:123]
	v_pk_mul_f32 v[122:123], v[52:53], v[122:123]
	v_mov_b32_e32 v133, v164
	v_mov_b32_e32 v161, v165
	v_mov_b32_e32 v157, v54
	v_mov_b32_e32 v163, v55
	v_pk_fma_f32 v[116:117], v[116:117], v[130:131], v[122:123] neg_lo:[0,0,1] neg_hi:[0,0,1]
	v_pk_add_f32 v[122:123], v[132:133], v[160:161] neg_lo:[0,1] neg_hi:[0,1]
	v_pk_fma_f32 v[52:53], v[52:53], v[130:131], v[126:127]
	v_pk_add_f32 v[54:55], v[156:157], v[162:163]
	v_lshl_add_u64 v[118:119], v[128:129], 0, s[4:5]
	global_load_dwordx4 v[130:133], v[90:91], off offset:128
	global_load_dwordx4 v[156:159], v[118:119], off offset:16
	s_mov_b64 s[4:5], 0x6080
	s_waitcnt vmcnt(1)
	v_mov_b32_e32 v90, v131
	v_mov_b32_e32 v131, v132
	s_waitcnt vmcnt(0)
	v_mul_f32_e32 v126, v86, v156
	v_mul_f32_e32 v132, v22, v157
	v_mul_f32_e32 v156, v22, v156
	v_mov_b32_e32 v22, v87
	v_mov_b32_e32 v91, v133
	v_pk_mul_f32 v[162:163], v[22:23], v[158:159]
	v_pk_mul_f32 v[118:119], v[84:85], v[90:91]
	v_pk_mul_f32 v[90:91], v[20:21], v[90:91]
	v_mul_f32_e32 v160, v86, v157
	v_mov_b32_e32 v127, v162
	v_mov_b32_e32 v133, v163
	v_mov_b32_e32 v86, v23
	v_pk_fma_f32 v[84:85], v[84:85], v[130:131], v[90:91] neg_lo:[0,0,1] neg_hi:[0,0,1]
	v_pk_add_f32 v[90:91], v[126:127], v[132:133] neg_lo:[0,1] neg_hi:[0,1]
	v_pk_mul_f32 v[22:23], v[86:87], v[158:159]
	v_add_co_u32_e32 v126, vcc, s24, v128
	v_mov_b32_e32 v157, v22
	v_mov_b32_e32 v161, v23
	v_addc_co_u32_e32 v127, vcc, 0, v129, vcc
	v_pk_fma_f32 v[20:21], v[20:21], v[130:131], v[118:119]
	v_pk_add_f32 v[22:23], v[156:157], v[160:161]
	v_lshl_add_u64 v[86:87], v[128:129], 0, s[28:29]
	global_load_dwordx4 v[130:133], v[126:127], off
	global_load_dwordx4 v[156:159], v[86:87], off offset:16
	s_waitcnt vmcnt(1)
	v_mov_b32_e32 v86, v131
	v_mov_b32_e32 v131, v132
	s_waitcnt vmcnt(0)
	v_mul_f32_e32 v118, v114, v156
	v_mul_f32_e32 v132, v50, v157
	v_mul_f32_e32 v162, v114, v157
	v_mul_f32_e32 v156, v50, v156
	v_mov_b32_e32 v50, v115
	v_mov_b32_e32 v114, v51
	v_mov_b32_e32 v87, v133
	v_pk_mul_f32 v[164:165], v[50:51], v[158:159]
	v_pk_mul_f32 v[50:51], v[114:115], v[158:159]
	v_pk_mul_f32 v[160:161], v[112:113], v[86:87]
	v_pk_mul_f32 v[86:87], v[48:49], v[86:87]
	v_mov_b32_e32 v119, v164
	v_mov_b32_e32 v133, v165
	v_mov_b32_e32 v157, v50
	v_mov_b32_e32 v163, v51
	v_pk_fma_f32 v[112:113], v[112:113], v[130:131], v[86:87] neg_lo:[0,0,1] neg_hi:[0,0,1]
	v_pk_add_f32 v[118:119], v[118:119], v[132:133] neg_lo:[0,1] neg_hi:[0,1]
	v_pk_fma_f32 v[48:49], v[48:49], v[130:131], v[160:161]
	v_pk_add_f32 v[50:51], v[156:157], v[162:163]
	v_lshl_add_u64 v[86:87], v[128:129], 0, s[4:5]
	global_load_dwordx4 v[130:133], v[126:127], off offset:128
	global_load_dwordx4 v[156:159], v[86:87], off offset:16
	s_mov_b64 s[4:5], 0x8000
	s_waitcnt vmcnt(1)
	v_mov_b32_e32 v86, v131
	v_mov_b32_e32 v131, v132
	s_waitcnt vmcnt(0)
	v_mul_f32_e32 v126, v82, v156
	v_mul_f32_e32 v132, v18, v157
	v_mul_f32_e32 v156, v18, v156
	v_mov_b32_e32 v18, v83
	v_mov_b32_e32 v87, v133
	v_mul_f32_e32 v160, v82, v157
	v_pk_mul_f32 v[162:163], v[18:19], v[158:159]
	v_mov_b32_e32 v82, v19
	v_pk_mul_f32 v[114:115], v[80:81], v[86:87]
	v_pk_mul_f32 v[86:87], v[16:17], v[86:87]
	v_mov_b32_e32 v127, v162
	v_mov_b32_e32 v133, v163
	v_pk_mul_f32 v[18:19], v[82:83], v[158:159]
	v_lshl_add_u64 v[82:83], v[128:129], 0, s[4:5]
	s_mov_b32 s4, 0x8000
	v_pk_fma_f32 v[80:81], v[80:81], v[130:131], v[86:87] neg_lo:[0,0,1] neg_hi:[0,0,1]
	v_pk_add_f32 v[86:87], v[126:127], v[132:133] neg_lo:[0,1] neg_hi:[0,1]
	v_add_co_u32_e32 v126, vcc, s4, v128
	v_mov_b32_e32 v157, v18
	v_mov_b32_e32 v161, v19
	v_addc_co_u32_e32 v127, vcc, 0, v129, vcc
	v_pk_fma_f32 v[16:17], v[16:17], v[130:131], v[114:115]
	v_pk_add_f32 v[18:19], v[156:157], v[160:161]
	global_load_dwordx4 v[130:133], v[126:127], off
	global_load_dwordx4 v[156:159], v[82:83], off offset:16
	s_mov_b64 s[4:5], 0x8080
	s_waitcnt vmcnt(1)
	v_mov_b32_e32 v82, v131
	v_mov_b32_e32 v131, v132
	s_waitcnt vmcnt(0)
	v_mul_f32_e32 v114, v110, v156
	v_mul_f32_e32 v132, v46, v157
	v_mul_f32_e32 v162, v110, v157
	v_mul_f32_e32 v156, v46, v156
	v_mov_b32_e32 v46, v111
	v_mov_b32_e32 v110, v47
	v_mov_b32_e32 v83, v133
	v_pk_mul_f32 v[164:165], v[46:47], v[158:159]
	v_pk_mul_f32 v[46:47], v[110:111], v[158:159]
	v_pk_mul_f32 v[160:161], v[108:109], v[82:83]
	v_pk_mul_f32 v[82:83], v[44:45], v[82:83]
	v_mov_b32_e32 v115, v164
	v_mov_b32_e32 v133, v165
	v_mov_b32_e32 v157, v46
	v_mov_b32_e32 v163, v47
	v_pk_fma_f32 v[108:109], v[108:109], v[130:131], v[82:83] neg_lo:[0,0,1] neg_hi:[0,0,1]
	v_pk_add_f32 v[114:115], v[114:115], v[132:133] neg_lo:[0,1] neg_hi:[0,1]
	v_pk_fma_f32 v[44:45], v[44:45], v[130:131], v[160:161]
	v_pk_add_f32 v[46:47], v[156:157], v[162:163]
	v_lshl_add_u64 v[82:83], v[128:129], 0, s[4:5]
	global_load_dwordx4 v[130:133], v[126:127], off offset:128
	global_load_dwordx4 v[156:159], v[82:83], off offset:16
	s_mov_b64 s[4:5], 0xa000
	s_waitcnt vmcnt(1)
	v_mov_b32_e32 v82, v131
	v_mov_b32_e32 v131, v132
	s_waitcnt vmcnt(0)
	v_mul_f32_e32 v126, v78, v156
	v_mul_f32_e32 v132, v14, v157
	v_mul_f32_e32 v156, v14, v156
	v_mov_b32_e32 v14, v79
	v_mov_b32_e32 v83, v133
	v_mul_f32_e32 v160, v78, v157
	v_pk_mul_f32 v[162:163], v[14:15], v[158:159]
	v_mov_b32_e32 v78, v15
	v_pk_mul_f32 v[110:111], v[76:77], v[82:83]
	v_pk_mul_f32 v[82:83], v[12:13], v[82:83]
	v_mov_b32_e32 v127, v162
	v_mov_b32_e32 v133, v163
	v_pk_mul_f32 v[14:15], v[78:79], v[158:159]
	v_lshl_add_u64 v[78:79], v[128:129], 0, s[4:5]
	s_mov_b32 s4, 0xa000
	v_pk_fma_f32 v[76:77], v[76:77], v[130:131], v[82:83] neg_lo:[0,0,1] neg_hi:[0,0,1]
	v_pk_add_f32 v[82:83], v[126:127], v[132:133] neg_lo:[0,1] neg_hi:[0,1]
	v_add_co_u32_e32 v126, vcc, s4, v128
	v_mov_b32_e32 v157, v14
	v_mov_b32_e32 v161, v15
	v_addc_co_u32_e32 v127, vcc, 0, v129, vcc
	v_pk_fma_f32 v[12:13], v[12:13], v[130:131], v[110:111]
	v_pk_add_f32 v[14:15], v[156:157], v[160:161]
	global_load_dwordx4 v[130:133], v[126:127], off
	global_load_dwordx4 v[156:159], v[78:79], off offset:16
	s_mov_b64 s[4:5], 0xa080
	s_waitcnt vmcnt(1)
	v_mov_b32_e32 v78, v131
	v_mov_b32_e32 v131, v132
	s_waitcnt vmcnt(0)
	v_mul_f32_e32 v110, v106, v156
	v_mul_f32_e32 v132, v42, v157
	v_mul_f32_e32 v162, v106, v157
	v_mul_f32_e32 v156, v42, v156
	v_mov_b32_e32 v42, v107
	v_mov_b32_e32 v106, v43
	v_mov_b32_e32 v79, v133
	v_pk_mul_f32 v[164:165], v[42:43], v[158:159]
	v_pk_mul_f32 v[42:43], v[106:107], v[158:159]
	v_pk_mul_f32 v[160:161], v[104:105], v[78:79]
	v_pk_mul_f32 v[78:79], v[40:41], v[78:79]
	v_mov_b32_e32 v111, v164
	v_mov_b32_e32 v133, v165
	v_mov_b32_e32 v157, v42
	v_mov_b32_e32 v163, v43
	v_pk_fma_f32 v[104:105], v[104:105], v[130:131], v[78:79] neg_lo:[0,0,1] neg_hi:[0,0,1]
	v_pk_add_f32 v[110:111], v[110:111], v[132:133] neg_lo:[0,1] neg_hi:[0,1]
	v_pk_fma_f32 v[40:41], v[40:41], v[130:131], v[160:161]
	v_pk_add_f32 v[42:43], v[156:157], v[162:163]
	v_lshl_add_u64 v[78:79], v[128:129], 0, s[4:5]
	global_load_dwordx4 v[130:133], v[126:127], off offset:128
	global_load_dwordx4 v[156:159], v[78:79], off offset:16
	s_mov_b64 s[4:5], 0xc000
	s_waitcnt vmcnt(1)
	v_mov_b32_e32 v78, v131
	v_mov_b32_e32 v131, v132
	s_waitcnt vmcnt(0)
	v_mul_f32_e32 v126, v74, v156
	v_mul_f32_e32 v132, v10, v157
	v_mul_f32_e32 v156, v10, v156
	v_mov_b32_e32 v10, v75
	v_mov_b32_e32 v79, v133
	v_mul_f32_e32 v160, v74, v157
	v_pk_mul_f32 v[162:163], v[10:11], v[158:159]
	v_mov_b32_e32 v74, v11
	v_pk_mul_f32 v[106:107], v[72:73], v[78:79]
	v_pk_mul_f32 v[78:79], v[8:9], v[78:79]
	v_mov_b32_e32 v127, v162
	v_mov_b32_e32 v133, v163
	v_pk_mul_f32 v[10:11], v[74:75], v[158:159]
	v_lshl_add_u64 v[74:75], v[128:129], 0, s[4:5]
	s_mov_b32 s4, 0xc000
	v_pk_fma_f32 v[72:73], v[72:73], v[130:131], v[78:79] neg_lo:[0,0,1] neg_hi:[0,0,1]
	v_pk_add_f32 v[78:79], v[126:127], v[132:133] neg_lo:[0,1] neg_hi:[0,1]
	v_add_co_u32_e32 v126, vcc, s4, v128
	v_mov_b32_e32 v157, v10
	v_mov_b32_e32 v161, v11
	v_addc_co_u32_e32 v127, vcc, 0, v129, vcc
	v_pk_fma_f32 v[8:9], v[8:9], v[130:131], v[106:107]
	v_pk_add_f32 v[10:11], v[156:157], v[160:161]
	global_load_dwordx4 v[130:133], v[126:127], off
	global_load_dwordx4 v[156:159], v[74:75], off offset:16
	s_mov_b64 s[4:5], 0xc080
	s_waitcnt vmcnt(1)
	v_mov_b32_e32 v74, v131
	v_mov_b32_e32 v131, v132
	s_waitcnt vmcnt(0)
	v_mul_f32_e32 v106, v102, v156
	v_mul_f32_e32 v132, v38, v157
	v_mul_f32_e32 v162, v102, v157
	v_mul_f32_e32 v156, v38, v156
	v_mov_b32_e32 v38, v103
	v_mov_b32_e32 v102, v39
	v_mov_b32_e32 v75, v133
	v_pk_mul_f32 v[164:165], v[38:39], v[158:159]
	v_pk_mul_f32 v[38:39], v[102:103], v[158:159]
	v_pk_mul_f32 v[160:161], v[100:101], v[74:75]
	v_pk_mul_f32 v[74:75], v[36:37], v[74:75]
	v_mov_b32_e32 v107, v164
	v_mov_b32_e32 v133, v165
	v_mov_b32_e32 v157, v38
	v_mov_b32_e32 v163, v39
	v_pk_fma_f32 v[100:101], v[100:101], v[130:131], v[74:75] neg_lo:[0,0,1] neg_hi:[0,0,1]
	v_pk_add_f32 v[106:107], v[106:107], v[132:133] neg_lo:[0,1] neg_hi:[0,1]
	v_pk_fma_f32 v[36:37], v[36:37], v[130:131], v[160:161]
	v_pk_add_f32 v[38:39], v[156:157], v[162:163]
	v_lshl_add_u64 v[74:75], v[128:129], 0, s[4:5]
	global_load_dwordx4 v[130:133], v[126:127], off offset:128
	global_load_dwordx4 v[156:159], v[74:75], off offset:16
	s_mov_b64 s[4:5], 0xe000
	s_waitcnt vmcnt(1)
	v_mov_b32_e32 v74, v131
	v_mov_b32_e32 v131, v132
	s_waitcnt vmcnt(0)
	v_mul_f32_e32 v126, v70, v156
	v_mul_f32_e32 v132, v6, v157
	v_mul_f32_e32 v156, v6, v156
	v_mov_b32_e32 v6, v71
	v_mov_b32_e32 v75, v133
	v_mul_f32_e32 v160, v70, v157
	v_pk_mul_f32 v[162:163], v[6:7], v[158:159]
	v_mov_b32_e32 v70, v7
	v_pk_mul_f32 v[102:103], v[68:69], v[74:75]
	v_pk_mul_f32 v[74:75], v[4:5], v[74:75]
	v_mov_b32_e32 v127, v162
	v_mov_b32_e32 v133, v163
	v_pk_mul_f32 v[6:7], v[70:71], v[158:159]
	v_lshl_add_u64 v[70:71], v[128:129], 0, s[4:5]
	s_mov_b32 s4, 0xe000
	v_pk_fma_f32 v[68:69], v[68:69], v[130:131], v[74:75] neg_lo:[0,0,1] neg_hi:[0,0,1]
	v_pk_add_f32 v[74:75], v[126:127], v[132:133] neg_lo:[0,1] neg_hi:[0,1]
	v_add_co_u32_e32 v126, vcc, s4, v128
	v_mov_b32_e32 v157, v6
	v_mov_b32_e32 v161, v7
	v_addc_co_u32_e32 v127, vcc, 0, v129, vcc
	v_pk_fma_f32 v[4:5], v[4:5], v[130:131], v[102:103]
	v_pk_add_f32 v[6:7], v[156:157], v[160:161]
	global_load_dwordx4 v[130:133], v[126:127], off
	global_load_dwordx4 v[156:159], v[70:71], off offset:16
	s_mov_b64 s[4:5], 0xe080
	s_waitcnt vmcnt(1)
	v_mov_b32_e32 v70, v131
	v_mov_b32_e32 v131, v132
	s_waitcnt vmcnt(0)
	v_mul_f32_e32 v102, v98, v156
	v_mul_f32_e32 v132, v34, v157
	v_mul_f32_e32 v156, v34, v156
	v_mov_b32_e32 v34, v99
	v_mov_b32_e32 v71, v133
	v_pk_mul_f32 v[164:165], v[34:35], v[158:159]
	v_pk_mul_f32 v[160:161], v[96:97], v[70:71]
	v_pk_mul_f32 v[70:71], v[32:33], v[70:71]
	v_mov_b32_e32 v103, v164
	v_mov_b32_e32 v133, v165
	v_pk_fma_f32 v[96:97], v[96:97], v[130:131], v[70:71] neg_lo:[0,0,1] neg_hi:[0,0,1]
	v_pk_add_f32 v[102:103], v[102:103], v[132:133] neg_lo:[0,1] neg_hi:[0,1]
	v_pk_fma_f32 v[32:33], v[32:33], v[130:131], v[160:161]
	v_lshl_add_u64 v[70:71], v[128:129], 0, s[4:5]
	global_load_dwordx4 v[126:129], v[126:127], off offset:128
	s_nop 0
	global_load_dwordx4 v[130:133], v[70:71], off offset:16
	v_mul_f32_e32 v162, v98, v157
	v_mov_b32_e32 v98, v35
	v_pk_mul_f32 v[34:35], v[98:99], v[158:159]
	s_waitcnt vmcnt(1)
	v_mov_b32_e32 v70, v127
	v_mov_b32_e32 v157, v34
	v_mov_b32_e32 v163, v35
	v_pk_add_f32 v[34:35], v[156:157], v[162:163]
	v_mov_b32_e32 v127, v128
	s_waitcnt vmcnt(0)
	v_mul_f32_e32 v128, v66, v130
	v_mul_f32_e32 v156, v2, v131
	v_mul_f32_e32 v130, v2, v130
	v_mov_b32_e32 v2, v67
	v_mov_b32_e32 v71, v129
	v_mul_f32_e32 v158, v66, v131
	v_pk_mul_f32 v[160:161], v[2:3], v[132:133]
	v_mov_b32_e32 v66, v3
	v_pk_mul_f32 v[98:99], v[64:65], v[70:71]
	v_pk_mul_f32 v[70:71], v[0:1], v[70:71]
	v_mov_b32_e32 v129, v160
	v_mov_b32_e32 v157, v161
	v_pk_mul_f32 v[2:3], v[66:67], v[132:133]
	v_pk_fma_f32 v[64:65], v[64:65], v[126:127], v[70:71] neg_lo:[0,0,1] neg_hi:[0,0,1]
	v_pk_add_f32 v[70:71], v[128:129], v[156:157] neg_lo:[0,1] neg_hi:[0,1]
	v_mov_b32_e32 v131, v2
	v_mov_b32_e32 v159, v3
	v_pk_fma_f32 v[0:1], v[0:1], v[126:127], v[98:99]
	v_pk_add_f32 v[2:3], v[130:131], v[158:159]
	v_mov_b32_e32 v66, v70
	v_mov_b32_e32 v67, v71
	v_mov_b32_e32 v70, v74
	v_mov_b32_e32 v71, v75
	v_mov_b32_e32 v74, v78
	v_mov_b32_e32 v75, v79
	v_mov_b32_e32 v78, v82
	v_mov_b32_e32 v79, v83
	v_mov_b32_e32 v82, v86
	v_mov_b32_e32 v83, v87
	v_mov_b32_e32 v86, v90
	v_mov_b32_e32 v87, v91
	v_mov_b32_e32 v90, v94
	v_mov_b32_e32 v91, v95
	v_mov_b32_e32 v94, v152
	v_mov_b32_e32 v95, v153
	v_mov_b32_e32 v98, v102
	v_mov_b32_e32 v99, v103
	v_mov_b32_e32 v102, v106
	v_mov_b32_e32 v103, v107
	v_mov_b32_e32 v106, v110
	v_mov_b32_e32 v107, v111
	v_mov_b32_e32 v110, v114
	v_mov_b32_e32 v111, v115
	v_mov_b32_e32 v114, v118
	v_mov_b32_e32 v115, v119
	v_mov_b32_e32 v118, v122
	v_mov_b32_e32 v119, v123
	v_mov_b32_e32 v122, v154
	v_mov_b32_e32 v123, v155
	v_mov_b32_e32 v126, v150
	v_mov_b32_e32 v127, v151
